# row_pre: g_ffn_post preloaded once + token-shift mix loop loads batched with counted vmcnt; ROW_P1 gain preload; MIX_O block-id rotation
# speedup vs baseline: 1.0166x; 1.0166x over previous
; __device__ __forceinline__ unsigned char* WSP() { return (unsigned char*)IN(41); }
; __device__ __forceinline__ int TID() { int t = threadIdx.x; asm volatile("" : "+v"(t)); return t; }
; __device__ __forceinline__ int BID() { int b = blockIdx.x; asm volatile("" : "+s"(b)); return b; }
; __device__ __forceinline__ int GSZ() { int g = gridDim.x; asm volatile("" : "+s"(g)); return g; }
; __device__ __forceinline__ int rfl(int v) { return __builtin_amdgcn_readfirstlane(v); }
; __device__ __forceinline__ void row_pre(const Params& p, int layer) {
;     const int tid_ = TID(), lane = tid_ & 63, wave_ = rfl(tid_ >> 6), bid_ = BID(), gw = bid_ * 8 + wave_, ngw = GSZ() * 8;
;     unsigned char* ws = WSP();
;     const bf16_t* Xold = (const bf16_t*)(ws + ((layer & 1) ? WS_XA : WS_XB));
;     bf16_t* Xnew = (bf16_t*)(ws + ((layer & 1) ? WS_XB : WS_XA));
;     const bf16_t* DOWN = (const bf16_t*)(ws + WS_MIX);
;     if (layer > 0) presum_sample_rows((bf16_t*)(ws + WS_MIX), bid_, tid_);
;     const float* gpost = IN(10) + (size_t)(layer - 1) * D;
;     const float* gpre = IN(7) + (size_t)layer * D;
;     const bool odd = layer & 1;
;     const int o = layer >> 1;
;     const int nit = (MP / 4 - gw + ngw - 1) / ngw;
.LBB0_624:
	s_ashr_i32 s2, s10, 6
	s_lshl_b32 s22, s12, 3
	s_add_i32 s22, s22, s2
	s_lshl_b32 s23, s11, 3
	s_and_b64 s[2:3], s[8:9], exec
	s_mov_b32 s2, 0xaa00000
	s_cselect_b32 s2, s2, 0x6800000
	v_writelane_b32 v234, s2, 26
	s_abs_i32 s2, s23
	v_cvt_f32_u32_e32 v0, s2
	s_sub_i32 s13, 0, s2
	s_sub_i32 s3, s23, s22
	s_addk_i32 s3, 0x7ff
	v_rcp_iflag_f32_e32 v0, v0
	s_xor_b32 s11, s3, s23
	s_abs_i32 s3, s3
	s_ashr_i32 s11, s11, 31
	v_mul_f32_e32 v0, 0x4f7ffffe, v0
	v_cvt_u32_f32_e32 v0, v0
	s_movk_i32 s5, 0x50
	s_mov_b32 s4, 56
	v_readfirstlane_b32 s16, v0
	s_mul_i32 s13, s13, s16
	s_mul_hi_u32 s13, s16, s13
	s_add_i32 s16, s16, s13
	s_mul_hi_u32 s13, s3, s16
	s_mul_i32 s16, s13, s2
	s_sub_i32 s3, s3, s16
	s_add_i32 s16, s13, 1
	s_sub_i32 s17, s3, s2
	s_cmp_ge_u32 s3, s2
	s_cselect_b32 s13, s16, s13
	s_cselect_b32 s3, s17, s3
	s_add_i32 s16, s13, 1
	s_cmp_ge_u32 s3, s2
	s_cselect_b32 s2, s16, s13
	s_xor_b32 s2, s2, s11
	s_sub_i32 s24, s2, s11
	s_cmp_lt_i32 s24, 0
	s_cbranch_scc1 .LBB0_688
	s_xor_b64 s[2:3], s[8:9], -1
	s_ashr_i32 s11, s5, 31
	s_add_u32 s16, s0, s5
	s_addc_u32 s17, s1, s11
	s_and_b64 s[18:19], s[8:9], exec
	s_mov_b32 s5, 0xaa00000
	s_cselect_b32 s5, 0x6800000, s5
	s_waitcnt lgkmcnt(0)
	s_add_u32 s18, s14, s5
	s_addc_u32 s19, s15, 0
	v_readlane_b32 s5, v234, 26
	v_readlane_b32 s30, v234, 19
	s_add_u32 s20, s14, s5
	v_readlane_b32 s31, v234, 20
	s_addc_u32 s21, s15, 0
	s_lshr_b64 s[26:27], s[30:31], 1
	s_lshr_b32 s5, s31, 1
	s_mul_i32 s5, s5, 0xc000
	s_mul_hi_u32 s11, s26, 0xc000
	s_add_i32 s34, s11, s5
	s_lshr_b32 s52, s30, 1
	s_ashr_i32 s5, s4, 31
	s_add_u32 s4, s0, s4
	s_addc_u32 s5, s1, s5
	s_load_dwordx2 s[4:5], s[4:5], 0x0
	s_nop 0
	s_load_dwordx2 s[16:17], s[16:17], 0x0
	s_lshl_b32 s11, s30, 13
	s_mul_i32 s35, s26, 0xc000
	s_mov_b32 s26, s30
	s_waitcnt lgkmcnt(0)
	s_add_u32 s4, s4, s11
	s_addc_u32 s5, s5, 0
	s_ashr_i32 s27, s30, 31
	s_lshl_b64 s[26:27], s[26:27], 13
	s_add_u32 s16, s16, s26
	s_addc_u32 s17, s17, s27
	v_lshlrev_b32_e32 v0, 2, v6
	s_cmp_lt_u32 s10, 64
	v_and_b32_e32 v72, 0xfc, v0
	s_cselect_b64 s[10:11], -1, 0
	s_cmp_lt_i32 s12, 64
	v_lshlrev_b32_e32 v2, 1, v72
	v_lshlrev_b32_e32 v4, 2, v72
	v_mov_b32_e32 v5, v3
	s_cselect_b64 s[26:27], -1, 0
	v_lshl_add_u64 v[0:1], s[14:15], 0, v[2:3]
	v_lshl_add_u64 v[82:83], s[4:5], 0, v[4:5]
	s_mov_b64 s[4:5], 0xec00000
	s_and_b64 s[10:11], s[10:11], s[26:27]
	s_add_i32 s26, s12, 0x800
	s_lshl_b64 s[12:13], s[52:53], 18
	v_lshl_add_u64 v[84:85], v[0:1], 0, s[4:5]
	s_lshl_b64 s[4:5], s[52:53], 16
	s_add_u32 s27, s4, 0x25c2000
	s_addc_u32 s28, s5, 0
	s_lshl_b64 s[4:5], s[52:53], 12
	s_add_u32 s30, s4, 0x25c0000
	s_addc_u32 s31, s5, 0
	s_movk_i32 s4, 0xf000
	v_lshl_add_u64 v[8:9], s[16:17], 0, v[4:5]
	s_mov_b32 s5, -1
	v_lshl_add_u64 v[86:87], v[8:9], 0, s[4:5]
	s_movk_i32 s4, 0xf400
	s_mov_b32 s5, -1
	v_lshl_add_u64 v[88:89], v[8:9], 0, s[4:5]
	s_movk_i32 s4, 0xf800
	s_mov_b32 s5, -1
	v_lshl_add_u64 v[90:91], v[8:9], 0, s[4:5]
	s_movk_i32 s4, 0xfc00
	s_mov_b32 s5, -1
	v_lshl_add_u64 v[74:75], s[18:19], 0, v[2:3]
	s_mov_b64 s[18:19], 0x10d00000
	v_lshl_add_u64 v[92:93], v[8:9], 0, s[4:5]
	s_mov_b64 s[4:5], 0x1400
	v_lshl_add_u64 v[76:77], v[0:1], 0, s[18:19]
	s_movk_i32 s16, 0xe000
	v_lshl_add_u64 v[96:97], v[82:83], 0, s[4:5]
	s_mov_b64 s[4:5], 0x1800
	v_and_b32_e32 v0, 63, v6
	s_mov_b32 s17, -1
	v_lshl_add_u64 v[80:81], s[20:21], 0, v[2:3]
	v_lshl_add_u64 v[98:99], v[82:83], 0, s[4:5]
	s_mov_b64 s[4:5], 0x1c00
	v_lshlrev_b32_e32 v2, 3, v0
	s_mov_b32 s25, 0
	v_lshl_add_u64 v[78:79], v[8:9], 0, s[16:17]
	v_lshl_add_u64 v[94:95], v[82:83], 0, s[56:57]
	v_lshl_add_u64 v[100:101], v[82:83], 0, s[4:5]
	v_lshl_or_b32 v102, v0, 4, s35
	v_mov_b32_e32 v103, s34
	v_lshl_add_u64 v[104:105], s[14:15], 0, v[2:3]
	s_andn2_b64 vcc, exec, s[40:41]
	s_cbranch_vccnz .Lrp_nopre
	global_load_dwordx4 v[196:199], v[78:79], off
	global_load_dwordx4 v[200:203], v[78:79], off offset:1024
	global_load_dwordx4 v[204:207], v[78:79], off offset:2048
	global_load_dwordx4 v[208:211], v[78:79], off offset:3072
	global_load_dwordx4 v[212:215], v[86:87], off
	global_load_dwordx4 v[216:219], v[88:89], off
	global_load_dwordx4 v[220:223], v[90:91], off
	global_load_dwordx4 v[224:227], v[92:93], off
.Lrp_nopre:
	s_branch .LBB0_628
.LBB0_626:
	s_add_i32 s14, s25, 1
	s_cmp_eq_u32 s25, s24
	s_cselect_b64 s[4:5], -1, 0
	s_mov_b32 s25, s14
	v_readlane_b32 s37, v234, 22

; __device__ __forceinline__ void row_load_bf16(const bf16_t* p, int lane, f32x4 (&v)[8]) {
; #pragma unroll
;     for (int j = 0; j < 8; ++j) { const u32x2 r = *(const u32x2*)(p + 256 * j + 4 * lane);
;         v[j][0] = __builtin_bit_cast(float, r.x << 16); v[j][1] = __builtin_bit_cast(float, r.x & 0xffff0000u); v[j][2] = __builtin_bit_cast(float, r.y << 16); v[j][3] = __builtin_bit_cast(float, r.y & 0xffff0000u); }
; }
; __device__ __forceinline__ float row_rstd(const f32x4 (&v)[8]) {
;     float s = 0.f;
; #pragma unroll
;     for (int j = 0; j < 8; ++j) s += (v[j][0] * v[j][0] + v[j][1] * v[j][1]) + (v[j][2] * v[j][2] + v[j][3] * v[j][3]);
;     return rsqrtf(wave_sum(s) * (1.f / D) + 1e-6f);
; __device__ __forceinline__ void row_pre(const Params& p, int layer) {
;     ...
;                 f32x4 dn[8]; row_load_bf16(DOWN + (size_t)m * D, lane, dn);
;                 const float rs = row_rstd(dn);
.LBB0_641:
	s_andn2_b64 vcc, exec, s[40:41]
	s_cbranch_vccnz .LBB0_662
	s_ashr_i32 s17, s16, 31
	s_lshl_b64 s[4:5], s[16:17], 12
	v_lshl_add_u64 v[68:69], v[76:77], 0, s[4:5]
	global_load_dwordx2 v[70:71], v[68:69], off
	global_load_dwordx2 v[112:113], v[68:69], off offset:512
	global_load_dwordx2 v[114:115], v[68:69], off offset:1024
	global_load_dwordx2 v[106:107], v[68:69], off offset:1536
	global_load_dwordx2 v[124:125], v[68:69], off offset:2048
	global_load_dwordx2 v[142:143], v[68:69], off offset:2560
	global_load_dwordx2 v[144:145], v[68:69], off offset:3072
	s_nop 0
	global_load_dwordx2 v[68:69], v[68:69], off offset:3584
	s_cmp_lt_i32 s37, 0
	s_waitcnt vmcnt(7)
	v_and_b32_e32 v141, 0xffff0000, v71
	v_and_b32_e32 v139, 0xffff0000, v70
	v_lshlrev_b32_e32 v140, 16, v71
	v_mul_f32_e32 v2, v141, v141
	s_waitcnt vmcnt(4)
	v_lshlrev_b32_e32 v121, 16, v106
	v_and_b32_e32 v119, 0xffff0000, v106
	v_lshlrev_b32_e32 v116, 16, v107
	v_and_b32_e32 v117, 0xffff0000, v107
	s_waitcnt vmcnt(0)
	v_lshlrev_b32_e32 v111, 16, v68
	v_and_b32_e32 v109, 0xffff0000, v68
	v_lshlrev_b32_e32 v106, 16, v69
	v_and_b32_e32 v107, 0xffff0000, v69
	v_lshlrev_b32_e32 v138, 16, v70
	v_pk_fma_f32 v[68:69], v[140:141], v[140:141], v[2:3] op_sel_hi:[1,1,0]
	v_and_b32_e32 v137, 0xffff0000, v113
	v_and_b32_e32 v136, 0xffff0000, v112
	v_mul_f32_e32 v2, v139, v139
	v_lshlrev_b32_e32 v131, 16, v113
	v_lshlrev_b32_e32 v130, 16, v112
	v_pk_mul_f32 v[70:71], v[136:137], v[136:137]
	v_pk_fma_f32 v[112:113], v[138:139], v[138:139], v[2:3] op_sel_hi:[1,1,0]
	v_pk_fma_f32 v[70:71], v[130:131], v[130:131], v[70:71]
	v_lshlrev_b32_e32 v126, 16, v114
	v_and_b32_e32 v127, 0xffff0000, v114
	v_lshlrev_b32_e32 v128, 16, v115
	v_and_b32_e32 v129, 0xffff0000, v115
	v_mov_b32_e32 v120, v112
	v_mov_b32_e32 v114, v68
	v_mov_b32_e32 v115, v121
	v_mul_f32_e32 v1, v119, v119
	v_pk_add_f32 v[68:69], v[112:113], v[68:69]
	v_pk_mul_f32 v[112:113], v[120:121], v[114:115]
	v_pk_add_f32 v[70:71], v[70:71], v[70:71] op_sel:[0,1] op_sel_hi:[1,0]
	v_mov_b32_e32 v69, v113
	v_mov_b32_e32 v71, v1
	v_mul_f32_e32 v2, v127, v127
	v_pk_add_f32 v[68:69], v[68:69], v[70:71]
	v_pk_fma_f32 v[70:71], v[126:127], v[126:127], v[2:3] op_sel_hi:[1,1,0]
	v_mul_f32_e32 v2, v129, v129
	v_mul_f32_e32 v73, v116, v116
	v_mul_f32_e32 v108, v117, v117
	v_pk_fma_f32 v[112:113], v[128:129], v[128:129], v[2:3] op_sel_hi:[1,1,0]
	v_mov_b32_e32 v71, v73
	v_mov_b32_e32 v113, v108
	v_pk_add_f32 v[70:71], v[70:71], v[112:113]
	v_lshlrev_b32_e32 v123, 16, v125
	v_lshlrev_b32_e32 v122, 16, v124
	v_and_b32_e32 v125, 0xffff0000, v125
	v_and_b32_e32 v124, 0xffff0000, v124
	v_pk_add_f32 v[158:159], v[68:69], v[70:71]
	v_pk_mul_f32 v[68:69], v[124:125], v[124:125]
	v_and_b32_e32 v115, 0xffff0000, v143
	v_pk_fma_f32 v[68:69], v[122:123], v[122:123], v[68:69]
	v_and_b32_e32 v114, 0xffff0000, v142
	v_pk_add_f32 v[160:161], v[68:69], v[68:69] op_sel:[0,1] op_sel_hi:[1,0]
	v_lshlrev_b32_e32 v113, 16, v143
	v_lshlrev_b32_e32 v112, 16, v142
	v_pk_mul_f32 v[68:69], v[114:115], v[114:115]
	v_lshlrev_b32_e32 v70, 16, v145
	v_pk_fma_f32 v[142:143], v[112:113], v[112:113], v[68:69]
	v_lshlrev_b32_e32 v68, 16, v144
	v_and_b32_e32 v69, 0xffff0000, v144
	v_and_b32_e32 v71, 0xffff0000, v145
	v_pk_add_f32 v[144:145], v[158:159], v[158:159] op_sel:[0,1] op_sel_hi:[1,0]
	v_mov_b32_e32 v158, v160
	v_mov_b32_e32 v110, v144
	v_mov_b32_e32 v159, v111
	v_mul_f32_e32 v1, v109, v109
	v_pk_add_f32 v[144:145], v[144:145], v[160:161]
	v_pk_mul_f32 v[158:159], v[110:111], v[158:159]
	v_pk_add_f32 v[142:143], v[142:143], v[142:143] op_sel:[0,1] op_sel_hi:[1,0]
	v_mov_b32_e32 v145, v159
	v_mov_b32_e32 v143, v1
	v_mul_f32_e32 v2, v69, v69
	v_pk_add_f32 v[142:143], v[144:145], v[142:143]
	v_pk_fma_f32 v[144:145], v[68:69], v[68:69], v[2:3] op_sel_hi:[1,1,0]
	v_mul_f32_e32 v2, v71, v71
	v_mul_f32_e32 v73, v106, v106
	v_mul_f32_e32 v108, v107, v107
	v_pk_fma_f32 v[158:159], v[70:71], v[70:71], v[2:3] op_sel_hi:[1,1,0]
	v_mov_b32_e32 v145, v73
	v_mov_b32_e32 v159, v108
	v_pk_add_f32 v[144:145], v[144:145], v[158:159]
	v_and_b32_e32 v2, 64, v152
	v_pk_add_f32 v[142:143], v[142:143], v[144:145]
	v_add_u32_e32 v2, 64, v2
	v_add_f32_e32 v1, v142, v143
	v_xor_b32_e32 v73, 1, v152
	v_cmp_lt_i32_e32 vcc, v73, v2
	v_mov_b32_e32 v118, v121
	v_mov_b32_e32 v120, v122
	v_cndmask_b32_e32 v73, v152, v73, vcc
	v_lshlrev_b32_e32 v73, 2, v73
	ds_bpermute_b32 v73, v73, v1
	v_mov_b32_e32 v121, v124
	v_mov_b32_e32 v124, v123
	v_mov_b32_e32 v108, v111
	s_waitcnt lgkmcnt(0)
; __device__ __forceinline__ float* OUTP() { return (float*)IN(40); }
; __device__ __forceinline__ unsigned pk2(float lo, float hi) { f32x2c v = {lo, hi}; return __builtin_bit_cast(unsigned, __builtin_convertvector(v, bf16x2c)); }
; __device__ __forceinline__ void row_pre(const Params& p, int layer) {
;     ...
;                 const float rs = row_rstd(dn);
; #pragma unroll
;                 for (int j = 0; j < 8; ++j) { const f32x4 g = *(const f32x4*)(gpost + 256 * j + 4 * lane); x[j] += dn[j] * rs * g; }
;                 if (r >= 0) {
; #pragma unroll
;                     for (int j = 0; j < 8; ++j) { if (layer == 4) *(f32x4*)(OUTP() + (size_t)m * D + 256 * j + 4 * lane) = x[j];
;                         else { u32x2 w; w.x = pk2(x[j][0], x[j][1]); w.y = pk2(x[j][2], x[j][3]); *(u32x2*)(Xnew + (size_t)m * D + 256 * j + 4 * lane) = w; } }
	v_add_f32_e32 v1, v1, v73
	v_xor_b32_e32 v73, 2, v152
	v_cmp_lt_i32_e32 vcc, v73, v2
	s_nop 1
	v_cndmask_b32_e32 v73, v152, v73, vcc
	v_lshlrev_b32_e32 v73, 2, v73
	ds_bpermute_b32 v73, v73, v1
	s_waitcnt lgkmcnt(0)
	v_add_f32_e32 v1, v1, v73
	v_xor_b32_e32 v73, 4, v152
	v_cmp_lt_i32_e32 vcc, v73, v2
	s_nop 1
	v_cndmask_b32_e32 v73, v152, v73, vcc
	v_lshlrev_b32_e32 v73, 2, v73
	ds_bpermute_b32 v73, v73, v1
	s_waitcnt lgkmcnt(0)
	v_add_f32_e32 v1, v1, v73
	v_xor_b32_e32 v73, 8, v152
	v_cmp_lt_i32_e32 vcc, v73, v2
	s_nop 1
	v_cndmask_b32_e32 v73, v152, v73, vcc
	v_lshlrev_b32_e32 v73, 2, v73
	ds_bpermute_b32 v73, v73, v1
	s_waitcnt lgkmcnt(0)
	v_add_f32_e32 v1, v1, v73
	v_xor_b32_e32 v73, 16, v152
	v_cmp_lt_i32_e32 vcc, v73, v2
	s_nop 1
	v_cndmask_b32_e32 v73, v152, v73, vcc
	v_lshlrev_b32_e32 v73, 2, v73
	ds_bpermute_b32 v73, v73, v1
	s_waitcnt lgkmcnt(0)
	v_add_f32_e32 v1, v1, v73
	v_xor_b32_e32 v73, 32, v152
	v_cmp_lt_i32_e32 vcc, v73, v2
	s_nop 1
	v_cndmask_b32_e32 v2, v152, v73, vcc
	v_lshlrev_b32_e32 v2, 2, v2
	ds_bpermute_b32 v2, v2, v1
	s_waitcnt lgkmcnt(0)
	v_add_f32_e32 v1, v1, v2
	v_fmamk_f32 v1, v1, 0x3a000000, v147
	v_cmp_gt_f32_e32 vcc, s29, v1
	v_mul_f32_e32 v2, 0x4b800000, v1
	s_nop 0
	v_cndmask_b32_e32 v1, v1, v2, vcc
	v_rsq_f32_e32 v1, v1
	s_nop 0
	v_mul_f32_e32 v2, 0x45800000, v1
	v_cndmask_b32_e32 v2, v1, v2, vcc
	v_pk_mul_f32 v[138:139], v[2:3], v[138:139] op_sel_hi:[0,1]
	v_pk_mul_f32 v[140:141], v[2:3], v[140:141] op_sel_hi:[0,1]
	v_pk_fma_f32 v[66:67], v[198:199], v[140:141], v[66:67]
	v_pk_fma_f32 v[64:65], v[196:197], v[138:139], v[64:65]
	v_mov_b32_e32 v142, v130
	v_mov_b32_e32 v143, v136
	v_pk_mul_f32 v[142:143], v[2:3], v[142:143] op_sel_hi:[0,1]
	v_mov_b32_e32 v136, v131
	v_pk_mul_f32 v[130:131], v[2:3], v[136:137] op_sel_hi:[0,1]
	v_pk_mul_f32 v[126:127], v[2:3], v[126:127] op_sel_hi:[0,1]
	v_pk_mul_f32 v[128:129], v[2:3], v[128:129] op_sel_hi:[0,1]
	v_pk_mul_f32 v[118:119], v[2:3], v[118:119] op_sel_hi:[0,1]
	v_pk_mul_f32 v[116:117], v[2:3], v[116:117] op_sel_hi:[0,1]
	v_pk_mul_f32 v[120:121], v[2:3], v[120:121] op_sel_hi:[0,1]
	v_pk_mul_f32 v[122:123], v[2:3], v[124:125] op_sel_hi:[0,1]
	v_pk_mul_f32 v[68:69], v[2:3], v[68:69] op_sel_hi:[0,1]
	v_pk_mul_f32 v[70:71], v[2:3], v[70:71] op_sel_hi:[0,1]
	v_pk_mul_f32 v[108:109], v[2:3], v[108:109] op_sel_hi:[0,1]
	v_pk_mul_f32 v[106:107], v[2:3], v[106:107] op_sel_hi:[0,1]
	v_pk_fma_f32 v[60:61], v[200:201], v[142:143], v[60:61]
	v_pk_fma_f32 v[62:63], v[202:203], v[130:131], v[62:63]
	v_pk_fma_f32 v[58:59], v[206:207], v[128:129], v[58:59]
	v_pk_fma_f32 v[56:57], v[204:205], v[126:127], v[56:57]
	v_pk_fma_f32 v[50:51], v[210:211], v[116:117], v[50:51]
	v_pk_fma_f32 v[48:49], v[208:209], v[118:119], v[48:49]
	v_pk_fma_f32 v[54:55], v[214:215], v[122:123], v[54:55]
	v_pk_fma_f32 v[52:53], v[212:213], v[120:121], v[52:53]
	v_mov_b32_e32 v121, v114
	v_mov_b32_e32 v114, v113
	v_mov_b32_e32 v120, v112
	v_pk_mul_f32 v[112:113], v[2:3], v[114:115] op_sel_hi:[0,1]
	v_pk_mul_f32 v[120:121], v[2:3], v[120:121] op_sel_hi:[0,1]
	v_pk_fma_f32 v[46:47], v[218:219], v[112:113], v[46:47]
	v_pk_fma_f32 v[44:45], v[216:217], v[120:121], v[44:45]
	v_pk_fma_f32 v[42:43], v[222:223], v[70:71], v[42:43]
	v_pk_fma_f32 v[40:41], v[220:221], v[68:69], v[40:41]
	v_pk_fma_f32 v[38:39], v[226:227], v[106:107], v[38:39]
	v_pk_fma_f32 v[36:37], v[224:225], v[108:109], v[36:37]
	s_cbranch_scc1 .LBB0_662
	s_lshl_b64 s[18:19], s[16:17], 11
	v_lshl_add_u64 v[68:69], s[18:19], 1, v[80:81]
	s_mov_b64 s[4:5], -1
	s_and_b64 vcc, exec, s[6:7]
	s_cbranch_vccz .LBB0_645
	v_cvt_pk_bf16_f32 v70, v64, v65
	v_cvt_pk_bf16_f32 v71, v66, v67
	global_store_dwordx2 v[68:69], v[70:71], off
	s_mov_b64 s[4:5], 0

; __device__ __forceinline__ float* OUTP() { return (float*)IN(40); }
; __device__ __forceinline__ unsigned pk2(float lo, float hi) { f32x2c v = {lo, hi}; return __builtin_bit_cast(unsigned, __builtin_convertvector(v, bf16x2c)); }
; __device__ __forceinline__ void row_pre(const Params& p, int layer) {
;     ...
;                 const float* mu = IN(17) + (size_t)o * 6 * D;
; #pragma unroll 1
;                 for (int i = 0; i < 6; ++i) {
;                     bf16_t* dst = (bf16_t*)(ws + WS_XMIX) + (size_t)i * M * D + (size_t)m * D;
; #pragma unroll
;                     for (int j = 0; j < 8; ++j) { const f32x4 mv = *(const f32x4*)(mu + (size_t)i * D + 256 * j + 4 * lane); const f32x4 y = x[j] + (hp[j] - x[j]) * mv;
;                         u32x2 w; w.x = pk2(y[0], y[1]); w.y = pk2(y[2], y[3]); *(u32x2*)(dst + 256 * j + 4 * lane) = w; }
;                 }
;                 if (t0 + r == Lseq - 1) {
;                     float* so = OUTP() + (m0 < MP ? OFF_SP + ((size_t)o * 2 + b) * D : OFF_SS + ((size_t)o * 32 + b) * D);
; #pragma unroll
;                     for (int j = 0; j < 8; ++j) *(f32x4*)(so + 256 * j + 4 * lane) = x[j];
;                 }
.LBB0_668:
	v_add_co_u32_e32 v110, vcc, 0xfffff000, v70
	v_lshl_add_u64 v[112:113], v[68:69], 0, s[4:5]
	s_nop 0
	v_addc_co_u32_e32 v111, vcc, -1, v71, vcc
	global_load_dwordx4 v[164:167], v[110:111], off offset:-3072
	global_load_dwordx4 v[168:171], v[110:111], off offset:-2048
	global_load_dwordx4 v[172:175], v[110:111], off offset:-1024
	global_load_dwordx4 v[176:179], v[70:71], off offset:-4096
	global_load_dwordx4 v[180:183], v[70:71], off offset:-3072
	global_load_dwordx4 v[184:187], v[70:71], off offset:-2048
	global_load_dwordx4 v[188:191], v[70:71], off offset:-1024
	global_load_dwordx4 v[192:195], v[70:71], off
	s_mov_b32 s16, 0x1b200000
	v_add_co_u32_e32 v112, vcc, s16, v112
	s_add_u32 s4, s4, 0x2100000
	s_nop 0
	v_addc_co_u32_e32 v113, vcc, 0, v113, vcc
	s_mov_b64 s[16:17], 0x2000
	s_addc_u32 s5, s5, 0
	s_cmp_eq_u32 s4, 0xc600000
	s_waitcnt vmcnt(7)
	v_pk_fma_f32 v[108:109], v[34:35], v[166:167], v[66:67]
	v_pk_fma_f32 v[106:107], v[32:33], v[164:165], v[64:65]
	s_nop 0
	v_cvt_pk_bf16_f32 v106, v106, v107
	v_cvt_pk_bf16_f32 v107, v108, v109
	global_store_dwordx2 v[112:113], v[106:107], off
	s_waitcnt vmcnt(7)
	v_pk_fma_f32 v[108:109], v[30:31], v[170:171], v[62:63]
	v_pk_fma_f32 v[106:107], v[28:29], v[168:169], v[60:61]
	s_nop 0
	v_cvt_pk_bf16_f32 v106, v106, v107
	v_cvt_pk_bf16_f32 v107, v108, v109
	global_store_dwordx2 v[112:113], v[106:107], off offset:512
	s_waitcnt vmcnt(7)
	v_pk_fma_f32 v[108:109], v[26:27], v[174:175], v[58:59]
	v_pk_fma_f32 v[106:107], v[24:25], v[172:173], v[56:57]
	s_nop 0
	v_cvt_pk_bf16_f32 v106, v106, v107
	v_cvt_pk_bf16_f32 v107, v108, v109
	global_store_dwordx2 v[112:113], v[106:107], off offset:1024
	s_waitcnt vmcnt(7)
	v_pk_fma_f32 v[108:109], v[18:19], v[178:179], v[50:51]
	v_pk_fma_f32 v[106:107], v[16:17], v[176:177], v[48:49]
	s_nop 0
	v_cvt_pk_bf16_f32 v106, v106, v107
	v_cvt_pk_bf16_f32 v107, v108, v109
	global_store_dwordx2 v[112:113], v[106:107], off offset:1536
	s_waitcnt vmcnt(7)
	v_pk_fma_f32 v[108:109], v[22:23], v[182:183], v[54:55]
	v_pk_fma_f32 v[106:107], v[20:21], v[180:181], v[52:53]
	s_nop 0
	v_cvt_pk_bf16_f32 v106, v106, v107
	v_cvt_pk_bf16_f32 v107, v108, v109
	global_store_dwordx2 v[112:113], v[106:107], off offset:2048
	s_waitcnt vmcnt(7)
	v_pk_fma_f32 v[108:109], v[14:15], v[186:187], v[46:47]
	v_pk_fma_f32 v[106:107], v[12:13], v[184:185], v[44:45]
	s_nop 0
	v_cvt_pk_bf16_f32 v106, v106, v107
	v_cvt_pk_bf16_f32 v107, v108, v109
	global_store_dwordx2 v[112:113], v[106:107], off offset:2560
	s_waitcnt vmcnt(7)
	v_pk_fma_f32 v[108:109], v[10:11], v[190:191], v[42:43]
	v_pk_fma_f32 v[106:107], v[8:9], v[188:189], v[40:41]
	s_nop 0
	v_cvt_pk_bf16_f32 v106, v106, v107
	v_cvt_pk_bf16_f32 v107, v108, v109
	global_store_dwordx2 v[112:113], v[106:107], off offset:3072
	v_lshl_add_u64 v[70:71], v[70:71], 0, s[16:17]
	s_waitcnt vmcnt(7)
	v_pk_fma_f32 v[108:109], v[6:7], v[194:195], v[38:39]
	v_pk_fma_f32 v[106:107], v[4:5], v[192:193], v[36:37]
	s_nop 0
	v_cvt_pk_bf16_f32 v106, v106, v107
	v_cvt_pk_bf16_f32 v107, v108, v109
	global_store_dwordx2 v[112:113], v[106:107], off offset:3584
	s_cbranch_scc0 .LBB0_668
	s_add_i32 s4, s37, s35
	s_cmp_eq_u32 s4, s36
	s_cbranch_scc0 .LBB0_672
	s_movk_i32 s4, 0x140
	s_ashr_i32 s5, s4, 31
	s_add_u32 s4, s0, s4
	s_addc_u32 s5, s1, s5
	s_load_dwordx2 s[4:5], s[4:5], 0x0
	v_lshlrev_b32_e32 v2, 2, v72
	s_waitcnt lgkmcnt(0)
	s_add_u32 s4, s4, s14
	s_addc_u32 s5, s5, s15
	v_lshl_add_u64 v[4:5], s[4:5], 0, v[2:3]
	v_add_co_u32_e32 v4, vcc, 0x1000, v4
	global_store_dwordx4 v2, v[64:67], s[4:5]
	global_store_dwordx4 v2, v[60:63], s[4:5] offset:1024
	global_store_dwordx4 v2, v[56:59], s[4:5] offset:2048
	global_store_dwordx4 v2, v[48:51], s[4:5] offset:3072
	v_addc_co_u32_e32 v5, vcc, 0, v5, vcc
	global_store_dwordx4 v[4:5], v[52:55], off
	global_store_dwordx4 v[4:5], v[44:47], off offset:1024
	global_store_dwordx4 v[4:5], v[40:43], off offset:2048
	global_store_dwordx4 v[4:5], v[36:39], off offset:3072
	s_branch .LBB0_672
